# attention: output-gate loads issued with the item's first loads (no other change vs v78)
# baseline (speedup 1.0000x reference)
.LBB0_188:
	s_or_b64 exec, exec, s[4:5]
	v_lshlrev_b32_e32 v176, 1, v125
	v_lshl_add_u64 v[32:33], v[126:127], 0, v[176:177]
	v_mov_b64_e32 v[46:47], v[156:157]
	v_mov_b64_e32 v[44:45], v[158:159]
	v_mov_b64_e32 v[42:43], v[160:161]
	v_mov_b64_e32 v[40:41], v[162:163]
	v_mov_b64_e32 v[38:39], v[164:165]
	v_mov_b64_e32 v[36:37], v[166:167]
	v_mov_b64_e32 v[34:35], v[168:169]
	s_nop 0
	v_mov_b64_e32 v[32:33], v[170:171]
	v_readlane_b32 s2, v254, 13
	v_readlane_b32 s3, v254, 14
	v_mov_b32_e32 v125, v177
	s_waitcnt vmcnt(7)
	v_lshlrev_b32_e32 v50, 16, v46
	v_and_b32_e32 v51, 0xffff0000, v46
	v_mul_f32_e32 v46, 0xbfb8aa3b, v50
	v_exp_f32_e32 v46, v46
	v_mov_b64_e32 v[48:49], s[2:3]
	v_mad_i64_i32 v[48:49], s[2:3], v136, s67, v[48:49]
	v_add_f32_e32 v46, 1.0, v46
	v_rcp_f32_e32 v52, v46
	v_mul_f32_e32 v46, 0xbfb8aa3b, v51
	v_exp_f32_e32 v46, v46
	v_lshl_add_u64 v[48:49], v[48:49], 0, v[124:125]
	v_add_f32_e32 v46, 1.0, v46
	v_rcp_f32_e32 v53, v46
	s_nop 0
	v_pk_mul_f32 v[50:51], v[52:53], v[50:51]
	s_nop 0
	v_pk_mul_f32 v[16:17], v[16:17], v[50:51]
	s_nop 0
	v_cvt_pk_bf16_f32 v46, v16, v17
	v_lshlrev_b32_e32 v16, 16, v47
	v_and_b32_e32 v17, 0xffff0000, v47
	v_mul_f32_e32 v47, 0xbfb8aa3b, v16
	v_exp_f32_e32 v47, v47
	s_nop 0
	v_add_f32_e32 v47, 1.0, v47
	v_rcp_f32_e32 v50, v47
	v_mul_f32_e32 v47, 0xbfb8aa3b, v17
	v_exp_f32_e32 v47, v47
	s_nop 0
	v_add_f32_e32 v47, 1.0, v47
	v_rcp_f32_e32 v51, v47
	s_nop 0
	v_pk_mul_f32 v[16:17], v[50:51], v[16:17]
	s_nop 0
	v_pk_mul_f32 v[16:17], v[18:19], v[16:17]
	s_waitcnt vmcnt(6)
	v_lshlrev_b32_e32 v18, 16, v44
	v_and_b32_e32 v19, 0xffff0000, v44
	v_mul_f32_e32 v44, 0xbfb8aa3b, v18
	v_exp_f32_e32 v44, v44
	v_cvt_pk_bf16_f32 v47, v16, v17
	v_lshl_add_u64 v[16:17], v[48:49], 0, v[176:177]
	global_store_dwordx2 v[16:17], v[46:47], off
	v_add_f32_e32 v44, 1.0, v44
	v_rcp_f32_e32 v46, v44
	v_mul_f32_e32 v44, 0xbfb8aa3b, v19
	v_exp_f32_e32 v44, v44
	s_nop 0
	v_add_f32_e32 v44, 1.0, v44
	v_rcp_f32_e32 v47, v44
	s_nop 0
	v_pk_mul_f32 v[18:19], v[46:47], v[18:19]
	s_nop 0
	v_pk_mul_f32 v[18:19], v[20:21], v[18:19]
	v_lshlrev_b32_e32 v20, 16, v45
	v_cvt_pk_bf16_f32 v18, v18, v19
	v_mul_f32_e32 v19, 0xbfb8aa3b, v20
	v_exp_f32_e32 v19, v19
	v_and_b32_e32 v21, 0xffff0000, v45
	v_add_f32_e32 v19, 1.0, v19
	v_rcp_f32_e32 v44, v19
	v_mul_f32_e32 v19, 0xbfb8aa3b, v21
	v_exp_f32_e32 v19, v19
	s_nop 0
	v_add_f32_e32 v19, 1.0, v19
	v_rcp_f32_e32 v45, v19
	s_nop 0
	v_pk_mul_f32 v[20:21], v[44:45], v[20:21]
	s_nop 0
	v_pk_mul_f32 v[20:21], v[22:23], v[20:21]
	s_nop 0
	v_cvt_pk_bf16_f32 v19, v20, v21
	global_store_dwordx2 v[16:17], v[18:19], off offset:16
	s_waitcnt vmcnt(7)
	v_lshlrev_b32_e32 v18, 16, v42
	v_and_b32_e32 v19, 0xffff0000, v42
	v_mul_f32_e32 v20, 0xbfb8aa3b, v18
	v_mul_f32_e32 v21, 0xbfb8aa3b, v19
	v_exp_f32_e32 v20, v20
	v_exp_f32_e32 v21, v21
	v_add_f32_e32 v20, 1.0, v20
	v_add_f32_e32 v21, 1.0, v21
	v_rcp_f32_e32 v20, v20
	v_rcp_f32_e32 v21, v21
	s_nop 0
	v_pk_mul_f32 v[18:19], v[20:21], v[18:19]
	s_nop 0
	v_pk_mul_f32 v[18:19], v[24:25], v[18:19]
	v_lshlrev_b32_e32 v20, 16, v43
	v_cvt_pk_bf16_f32 v18, v18, v19
	v_mul_f32_e32 v19, 0xbfb8aa3b, v20
	v_exp_f32_e32 v19, v19
	v_and_b32_e32 v21, 0xffff0000, v43
	v_add_f32_e32 v19, 1.0, v19
	v_rcp_f32_e32 v22, v19
	v_mul_f32_e32 v19, 0xbfb8aa3b, v21
	v_exp_f32_e32 v19, v19
	s_nop 0
	v_add_f32_e32 v19, 1.0, v19
	v_rcp_f32_e32 v23, v19
	s_nop 0
	v_pk_mul_f32 v[20:21], v[22:23], v[20:21]
	s_nop 0
	v_pk_mul_f32 v[20:21], v[26:27], v[20:21]
	s_nop 0
	v_cvt_pk_bf16_f32 v19, v20, v21
	global_store_dwordx2 v[16:17], v[18:19], off offset:32
	s_waitcnt vmcnt(7)
	v_lshlrev_b32_e32 v18, 16, v40
	v_and_b32_e32 v19, 0xffff0000, v40
	v_mul_f32_e32 v20, 0xbfb8aa3b, v18
	v_mul_f32_e32 v21, 0xbfb8aa3b, v19
	v_exp_f32_e32 v20, v20
	v_exp_f32_e32 v21, v21
	v_add_f32_e32 v20, 1.0, v20
	v_add_f32_e32 v21, 1.0, v21
	v_rcp_f32_e32 v20, v20
	v_rcp_f32_e32 v21, v21
	s_nop 0
	v_pk_mul_f32 v[18:19], v[20:21], v[18:19]
	s_nop 0
	v_pk_mul_f32 v[18:19], v[28:29], v[18:19]
	v_lshlrev_b32_e32 v20, 16, v41
	v_cvt_pk_bf16_f32 v18, v18, v19
	v_mul_f32_e32 v19, 0xbfb8aa3b, v20
	v_exp_f32_e32 v19, v19
	v_and_b32_e32 v21, 0xffff0000, v41
	v_add_f32_e32 v19, 1.0, v19
	v_rcp_f32_e32 v22, v19
	v_mul_f32_e32 v19, 0xbfb8aa3b, v21
	v_exp_f32_e32 v19, v19
	s_nop 0
	v_add_f32_e32 v19, 1.0, v19
	v_rcp_f32_e32 v23, v19
	s_nop 0
	v_pk_mul_f32 v[20:21], v[22:23], v[20:21]
	s_nop 0
	v_pk_mul_f32 v[20:21], v[30:31], v[20:21]
	s_nop 0
	v_cvt_pk_bf16_f32 v19, v20, v21
	global_store_dwordx2 v[16:17], v[18:19], off offset:48
	s_waitcnt vmcnt(7)
	v_lshlrev_b32_e32 v18, 16, v38
	v_and_b32_e32 v19, 0xffff0000, v38
	v_mul_f32_e32 v20, 0xbfb8aa3b, v18
	v_mul_f32_e32 v21, 0xbfb8aa3b, v19
	v_exp_f32_e32 v20, v20
	v_exp_f32_e32 v21, v21
	v_add_f32_e32 v20, 1.0, v20
	v_add_f32_e32 v21, 1.0, v21
	v_rcp_f32_e32 v20, v20
	v_rcp_f32_e32 v21, v21
	s_nop 0
	v_pk_mul_f32 v[18:19], v[20:21], v[18:19]
	s_nop 0
	v_pk_mul_f32 v[0:1], v[0:1], v[18:19]
	v_lshlrev_b32_e32 v18, 16, v39
	v_cvt_pk_bf16_f32 v0, v0, v1
	v_mul_f32_e32 v1, 0xbfb8aa3b, v18
	v_exp_f32_e32 v1, v1
	v_and_b32_e32 v19, 0xffff0000, v39
	v_add_f32_e32 v1, 1.0, v1
	v_rcp_f32_e32 v20, v1
	v_mul_f32_e32 v1, 0xbfb8aa3b, v19
	v_exp_f32_e32 v1, v1
	s_nop 0
	v_add_f32_e32 v1, 1.0, v1
	v_rcp_f32_e32 v21, v1
	s_nop 0
	v_pk_mul_f32 v[18:19], v[20:21], v[18:19]
	s_nop 0
	v_pk_mul_f32 v[2:3], v[2:3], v[18:19]
	s_nop 0
	v_cvt_pk_bf16_f32 v1, v2, v3
	global_store_dwordx2 v[16:17], v[0:1], off offset:64
	s_waitcnt vmcnt(7)
	v_lshlrev_b32_e32 v0, 16, v36
	v_and_b32_e32 v1, 0xffff0000, v36
	v_mul_f32_e32 v2, 0xbfb8aa3b, v0
	v_mul_f32_e32 v3, 0xbfb8aa3b, v1
	v_exp_f32_e32 v2, v2
	v_exp_f32_e32 v3, v3
	v_add_f32_e32 v2, 1.0, v2
	v_add_f32_e32 v3, 1.0, v3
	v_rcp_f32_e32 v2, v2
	v_rcp_f32_e32 v3, v3
	s_nop 0
	v_pk_mul_f32 v[0:1], v[2:3], v[0:1]
	s_nop 0
	v_pk_mul_f32 v[0:1], v[4:5], v[0:1]
	v_lshlrev_b32_e32 v2, 16, v37
	v_cvt_pk_bf16_f32 v0, v0, v1
	v_mul_f32_e32 v1, 0xbfb8aa3b, v2
	v_exp_f32_e32 v1, v1
	v_and_b32_e32 v3, 0xffff0000, v37
	v_add_f32_e32 v1, 1.0, v1
	v_rcp_f32_e32 v4, v1
	v_mul_f32_e32 v1, 0xbfb8aa3b, v3
	v_exp_f32_e32 v1, v1
	s_nop 0
	v_add_f32_e32 v1, 1.0, v1
	v_rcp_f32_e32 v5, v1
	s_nop 0
	v_pk_mul_f32 v[2:3], v[4:5], v[2:3]
	s_nop 0
	v_pk_mul_f32 v[2:3], v[6:7], v[2:3]
	s_nop 0
	v_cvt_pk_bf16_f32 v1, v2, v3
	global_store_dwordx2 v[16:17], v[0:1], off offset:80
	s_waitcnt vmcnt(7)
	v_lshlrev_b32_e32 v0, 16, v34
	v_and_b32_e32 v1, 0xffff0000, v34
	v_mul_f32_e32 v2, 0xbfb8aa3b, v0
	v_mul_f32_e32 v3, 0xbfb8aa3b, v1
	v_exp_f32_e32 v2, v2
	v_exp_f32_e32 v3, v3
	v_add_f32_e32 v2, 1.0, v2
	v_add_f32_e32 v3, 1.0, v3
	v_rcp_f32_e32 v2, v2
	v_rcp_f32_e32 v3, v3
	s_nop 0
	v_pk_mul_f32 v[0:1], v[2:3], v[0:1]
	s_nop 0
	v_pk_mul_f32 v[0:1], v[8:9], v[0:1]
	v_lshlrev_b32_e32 v2, 16, v35
	v_cvt_pk_bf16_f32 v0, v0, v1
	v_mul_f32_e32 v1, 0xbfb8aa3b, v2
	v_exp_f32_e32 v1, v1
	v_and_b32_e32 v3, 0xffff0000, v35
	v_add_f32_e32 v1, 1.0, v1
	v_rcp_f32_e32 v4, v1
	v_mul_f32_e32 v1, 0xbfb8aa3b, v3
	v_exp_f32_e32 v1, v1
	s_nop 0
	v_add_f32_e32 v1, 1.0, v1
	v_rcp_f32_e32 v5, v1
	s_nop 0
	v_pk_mul_f32 v[2:3], v[4:5], v[2:3]
	s_nop 0
	v_pk_mul_f32 v[2:3], v[10:11], v[2:3]
	s_nop 0
	v_cvt_pk_bf16_f32 v1, v2, v3
	global_store_dwordx2 v[16:17], v[0:1], off offset:96
	s_waitcnt vmcnt(7)
	v_lshlrev_b32_e32 v0, 16, v32
	v_and_b32_e32 v1, 0xffff0000, v32
	v_mul_f32_e32 v2, 0xbfb8aa3b, v0
	v_mul_f32_e32 v3, 0xbfb8aa3b, v1
	v_exp_f32_e32 v2, v2
	v_exp_f32_e32 v3, v3
	v_add_f32_e32 v2, 1.0, v2
	v_add_f32_e32 v3, 1.0, v3
	v_rcp_f32_e32 v2, v2
	v_rcp_f32_e32 v3, v3
	s_nop 0
	v_pk_mul_f32 v[0:1], v[2:3], v[0:1]
	s_nop 0
	v_pk_mul_f32 v[0:1], v[12:13], v[0:1]
	v_lshlrev_b32_e32 v2, 16, v33
	v_cvt_pk_bf16_f32 v0, v0, v1
	v_mul_f32_e32 v1, 0xbfb8aa3b, v2
	v_exp_f32_e32 v1, v1
	v_and_b32_e32 v3, 0xffff0000, v33
	v_add_f32_e32 v1, 1.0, v1
	v_rcp_f32_e32 v4, v1
	v_mul_f32_e32 v1, 0xbfb8aa3b, v3
	v_exp_f32_e32 v1, v1
	s_nop 0
	v_add_f32_e32 v1, 1.0, v1
	v_rcp_f32_e32 v5, v1
	s_nop 0
	v_pk_mul_f32 v[2:3], v[4:5], v[2:3]
	s_nop 0
	v_pk_mul_f32 v[2:3], v[14:15], v[2:3]
	s_nop 0
	v_cvt_pk_bf16_f32 v1, v2, v3
	global_store_dwordx2 v[16:17], v[0:1], off offset:112

.LBB0_297:
	s_or_b64 exec, exec, s[2:3]
	v_and_b32_e32 v6, 64, v210
	v_xor_b32_e32 v5, 32, v210
	v_add_u32_e32 v6, 64, v6
	v_cmp_lt_i32_e32 vcc, v5, v6
	v_lshlrev_b32_e32 v125, 2, v4
	v_cmp_lt_u32_e64 s[38:39], v125, v137
	v_cndmask_b32_e32 v5, v210, v5, vcc
	v_lshlrev_b32_e32 v139, 2, v5
	v_cmp_eq_u32_e32 vcc, 0, v4
	v_lshlrev_b32_e32 v172, 1, v125
	v_mov_b32_e32 v173, 0
	v_lshl_add_u64 v[174:175], v[126:127], 0, v[172:173]
	global_load_dwordx2 v[156:157], v[174:175], off offset:1024
	global_load_dwordx2 v[158:159], v[174:175], off offset:1040
	global_load_dwordx2 v[160:161], v[174:175], off offset:1056
	global_load_dwordx2 v[162:163], v[174:175], off offset:1072
	global_load_dwordx2 v[164:165], v[174:175], off offset:1088
	global_load_dwordx2 v[166:167], v[174:175], off offset:1104
	global_load_dwordx2 v[168:169], v[174:175], off offset:1120
	global_load_dwordx2 v[170:171], v[174:175], off offset:1136
	s_waitcnt vmcnt(0)
	v_mfma_f32_32x32x16_bf16 v[0:15], v[0:3], v[48:51], 0
	v_mfma_f32_32x32x16_bf16 v[0:15], v[28:31], v[52:55], v[0:15]
	v_mfma_f32_32x32x16_bf16 v[0:15], v[20:23], v[56:59], v[0:15]
	v_mfma_f32_32x32x16_bf16 v[0:15], v[24:27], v[60:63], v[0:15]
	s_nop 11
	v_mul_f32_e32 v0, 0x3e38aa3b, v0
	v_min_f32_e32 v0, 0x42700000, v0
	v_exp_f32_e32 v20, v0
	s_nop 0
	v_add_f32_e32 v20, 1.0, v20
	v_log_f32_e32 v21, v20
	s_nop 0
	v_sub_f32_e32 v0, v0, v21
	v_cndmask_b32_e64 v20, v217, v0, s[38:39]
	v_mul_f32_e32 v0, 0x3e38aa3b, v1
	v_min_f32_e32 v0, 0x42700000, v0
	v_exp_f32_e32 v1, v0
	v_cndmask_b32_e64 v23, 0, v21, s[38:39]
	v_or_b32_e32 v21, 1, v125
	v_cmp_lt_u32_e64 s[38:39], v21, v137
	v_add_f32_e32 v1, 1.0, v1
	v_log_f32_e32 v1, v1
	s_nop 0
	v_sub_f32_e32 v0, v0, v1
	v_cndmask_b32_e64 v22, v217, v0, s[38:39]
	v_mul_f32_e32 v0, 0x3e38aa3b, v2
	v_min_f32_e32 v0, 0x42700000, v0
	v_cndmask_b32_e64 v21, 0, v1, s[38:39]
	v_exp_f32_e32 v1, v0
	v_or_b32_e32 v2, 2, v125
	v_cmp_lt_u32_e64 s[38:39], v2, v137
	v_or_b32_e32 v2, 3, v125
	v_add_f32_e32 v1, 1.0, v1
	v_log_f32_e32 v1, v1
	s_nop 0
	v_sub_f32_e32 v0, v0, v1
	v_cndmask_b32_e64 v25, v217, v0, s[38:39]
	v_mul_f32_e32 v0, 0x3e38aa3b, v3
	v_min_f32_e32 v0, 0x42700000, v0
	v_cndmask_b32_e64 v24, 0, v1, s[38:39]
	v_exp_f32_e32 v1, v0
	v_cmp_lt_u32_e64 s[38:39], v2, v137
	v_or_b32_e32 v2, 8, v125
	v_or_b32_e32 v3, 9, v125
	v_add_f32_e32 v1, 1.0, v1
	v_log_f32_e32 v1, v1
	s_nop 0
	v_sub_f32_e32 v0, v0, v1
	v_cndmask_b32_e64 v27, v217, v0, s[38:39]
	v_mul_f32_e32 v0, 0x3e38aa3b, v4
	v_min_f32_e32 v0, 0x42700000, v0
	v_cndmask_b32_e64 v26, 0, v1, s[38:39]
	v_exp_f32_e32 v1, v0
	v_cmp_lt_u32_e64 s[38:39], v2, v137
	v_or_b32_e32 v4, 10, v125
	v_add_f32_e32 v1, 1.0, v1
	v_log_f32_e32 v1, v1
	s_nop 0
	v_sub_f32_e32 v0, v0, v1
	v_cndmask_b32_e64 v28, v217, v0, s[38:39]
	v_mul_f32_e32 v0, 0x3e38aa3b, v5
	v_min_f32_e32 v0, 0x42700000, v0
	v_cndmask_b32_e64 v2, 0, v1, s[38:39]
	v_exp_f32_e32 v1, v0
	v_cmp_lt_u32_e64 s[38:39], v3, v137
	v_or_b32_e32 v5, 18, v125
	v_add_f32_e32 v1, 1.0, v1
	v_log_f32_e32 v1, v1
	s_nop 0
	v_sub_f32_e32 v0, v0, v1
	v_cndmask_b32_e64 v29, v217, v0, s[38:39]
	v_cndmask_b32_e64 v0, 0, v1, s[38:39]
	v_mul_f32_e32 v1, 0x3e38aa3b, v6
	v_min_f32_e32 v1, 0x42700000, v1
	v_exp_f32_e32 v3, v1
	v_cmp_lt_u32_e64 s[38:39], v4, v137
	v_or_b32_e32 v4, 11, v125
	v_add_f32_e32 v3, 1.0, v3
	v_log_f32_e32 v3, v3
	s_nop 0
	v_sub_f32_e32 v1, v1, v3
	v_cndmask_b32_e64 v31, v217, v1, s[38:39]
	v_mul_f32_e32 v1, 0x3e38aa3b, v7
	v_min_f32_e32 v1, 0x42700000, v1
	v_cndmask_b32_e64 v30, 0, v3, s[38:39]
	v_exp_f32_e32 v3, v1
	v_cmp_lt_u32_e64 s[38:39], v4, v137
	v_or_b32_e32 v4, 16, v125
	v_or_b32_e32 v7, 25, v125
	v_add_f32_e32 v3, 1.0, v3
	v_log_f32_e32 v3, v3
	s_nop 0
	v_sub_f32_e32 v1, v1, v3
	v_cndmask_b32_e64 v96, v217, v1, s[38:39]
	v_mul_f32_e32 v1, 0x3e38aa3b, v8
	v_min_f32_e32 v1, 0x42700000, v1
	v_cndmask_b32_e64 v97, 0, v3, s[38:39]
	v_exp_f32_e32 v3, v1
	v_cmp_lt_u32_e64 s[38:39], v4, v137
	v_or_b32_e32 v4, 17, v125
	v_add_f32_e32 v8, v30, v97
	v_add_f32_e32 v3, 1.0, v3
	v_log_f32_e32 v3, v3
	s_nop 0
	v_sub_f32_e32 v1, v1, v3
	v_cndmask_b32_e64 v98, v217, v1, s[38:39]
	v_mul_f32_e32 v1, 0x3e38aa3b, v9
	v_min_f32_e32 v1, 0x42700000, v1
	v_cndmask_b32_e64 v6, 0, v3, s[38:39]
	v_exp_f32_e32 v3, v1
	v_cmp_lt_u32_e64 s[38:39], v4, v137
	v_add_f32_e32 v3, 1.0, v3
	v_log_f32_e32 v3, v3
	s_nop 0
	v_sub_f32_e32 v1, v1, v3
	v_cndmask_b32_e64 v99, v217, v1, s[38:39]
	v_mul_f32_e32 v1, 0x3e38aa3b, v10
	v_min_f32_e32 v1, 0x42700000, v1
	v_cndmask_b32_e64 v4, 0, v3, s[38:39]
	v_exp_f32_e32 v3, v1
	v_cmp_lt_u32_e64 s[38:39], v5, v137
	v_or_b32_e32 v5, 19, v125
	v_add_f32_e32 v3, 1.0, v3
	v_log_f32_e32 v3, v3
	s_nop 0
	v_sub_f32_e32 v1, v1, v3
	v_cndmask_b32_e64 v100, v217, v1, s[38:39]
	v_mul_f32_e32 v1, 0x3e38aa3b, v11
	v_min_f32_e32 v1, 0x42700000, v1
	v_cndmask_b32_e64 v101, 0, v3, s[38:39]
	v_exp_f32_e32 v3, v1
	v_cmp_lt_u32_e64 s[38:39], v5, v137
	v_or_b32_e32 v5, 24, v125
	v_add_f32_e32 v3, 1.0, v3
	v_log_f32_e32 v3, v3
	s_nop 0
	v_sub_f32_e32 v1, v1, v3
	v_cndmask_b32_e64 v102, v217, v1, s[38:39]
	v_mul_f32_e32 v1, 0x3e38aa3b, v12
	v_min_f32_e32 v1, 0x42700000, v1
	v_cndmask_b32_e64 v103, 0, v3, s[38:39]
	v_exp_f32_e32 v3, v1
	v_cmp_lt_u32_e64 s[38:39], v5, v137
	v_add_f32_e32 v10, v101, v103
	v_add_f32_e32 v3, 1.0, v3
	v_log_f32_e32 v3, v3
	s_nop 0
	v_sub_f32_e32 v1, v1, v3
	v_cndmask_b32_e64 v12, v217, v1, s[38:39]
	v_cndmask_b32_e64 v1, 0, v3, s[38:39]
	v_mul_f32_e32 v3, 0x3e38aa3b, v13
	v_min_f32_e32 v3, 0x42700000, v3
	v_exp_f32_e32 v5, v3
	v_cmp_lt_u32_e64 s[38:39], v7, v137
	v_or_b32_e32 v7, 26, v125
	v_add_f32_e32 v5, 1.0, v5
	v_log_f32_e32 v5, v5
	s_nop 0
	v_sub_f32_e32 v3, v3, v5
	v_cndmask_b32_e64 v13, v217, v3, s[38:39]
	v_mul_f32_e32 v3, 0x3e38aa3b, v14
	v_min_f32_e32 v3, 0x42700000, v3
	v_cndmask_b32_e64 v104, 0, v5, s[38:39]
	v_exp_f32_e32 v5, v3
	v_cmp_lt_u32_e64 s[38:39], v7, v137
	v_or_b32_e32 v7, 27, v125
	v_add_f32_e32 v5, 1.0, v5
	v_log_f32_e32 v5, v5
	s_nop 0
	v_sub_f32_e32 v3, v3, v5
	v_cndmask_b32_e64 v14, v217, v3, s[38:39]
	v_mul_f32_e32 v3, 0x3e38aa3b, v15
	v_min_f32_e32 v3, 0x42700000, v3
	v_cndmask_b32_e64 v105, 0, v5, s[38:39]
	v_exp_f32_e32 v5, v3
	v_cmp_lt_u32_e64 s[38:39], v7, v137
	v_add_f32_e32 v7, v1, v104
	v_add_f32_e32 v5, 1.0, v5
	v_log_f32_e32 v5, v5
	s_nop 0
	v_sub_f32_e32 v3, v3, v5
	v_cndmask_b32_e64 v15, v217, v3, s[38:39]
	v_cndmask_b32_e64 v106, 0, v5, s[38:39]
	v_add_f32_e32 v3, v23, v21
	v_add_f32_e32 v5, v24, v26
	v_add_f32_e32 v93, v3, v5
	v_add_f32_e32 v5, v105, v106
	v_pk_add_f32 v[6:7], v[6:7], v[4:5]
	ds_bpermute_b32 v11, v139, v7
	ds_bpermute_b32 v94, v139, v93
	s_waitcnt lgkmcnt(1)
	v_pk_add_f32 v[6:7], v[6:7], v[10:11]
	ds_bpermute_b32 v9, v139, v6
	v_mov_b32_e32 v3, v6
	v_mov_b32_e32 v1, v7
	v_pk_add_f32 v[2:3], v[2:3], v[0:1]
	s_waitcnt lgkmcnt(0)
	v_pk_add_f32 v[2:3], v[2:3], v[8:9]
	ds_bpermute_b32 v1, v139, v2
	v_add_f32_e32 v2, v2, v3
	s_waitcnt lgkmcnt(0)
	v_add_f32_e32 v95, v2, v1
	v_cndmask_b32_e32 v1, 0, v1, vcc
	v_add_f32_e32 v1, v1, v3
	v_cndmask_b32_e32 v2, 0, v94, vcc
	v_add_f32_e32 v1, 0, v1
	v_add_f32_e32 v2, v2, v95
	v_sub_f32_e32 v3, v96, v1
	v_add_f32_e32 v1, v97, v1
	v_add_f32_e32 v2, 0, v2
	v_sub_f32_e32 v10, v31, v1
	v_add_f32_e32 v1, v30, v1
	v_sub_f32_e32 v5, v27, v2
	v_add_f32_e32 v2, v26, v2
	v_add_f32_e32 v0, v0, v1
	v_sub_f32_e32 v6, v25, v2
	v_add_f32_e32 v2, v24, v2
	v_sub_f32_e32 v0, v28, v0
	v_sub_f32_e32 v8, v22, v2
	v_add_f32_e32 v2, v21, v2
	v_exp_f32_e32 v21, v0
	v_cndmask_b32_e32 v0, 0, v9, vcc
	v_add_f32_e32 v0, v0, v7
	v_add_f32_e32 v0, 0, v0
	v_sub_f32_e32 v2, v20, v2
	v_sub_f32_e32 v20, v29, v1
	v_sub_f32_e32 v1, v102, v0
	v_add_f32_e32 v0, v103, v0
	v_exp_f32_e32 v96, v1
	v_sub_f32_e32 v1, v100, v0
	v_add_f32_e32 v0, v101, v0
	v_exp_f32_e32 v97, v1
	v_sub_f32_e32 v1, v99, v0
	v_add_f32_e32 v0, v4, v0
	v_sub_f32_e32 v0, v98, v0
	v_exp_f32_e32 v98, v0
	v_add_f32_e32 v0, 0, v11
	v_cndmask_b32_e32 v0, 0, v0, vcc
	v_exp_f32_e32 v5, v5
	v_exp_f32_e32 v6, v6
	v_exp_f32_e32 v8, v8
	v_exp_f32_e32 v2, v2
	v_exp_f32_e32 v3, v3
	v_exp_f32_e32 v10, v10
	v_exp_f32_e32 v20, v20
	v_exp_f32_e32 v99, v1
	v_sub_f32_e32 v1, v15, v0
	v_add_f32_e32 v0, v0, v106
	v_exp_f32_e32 v100, v1
	v_sub_f32_e32 v1, v14, v0
	v_add_f32_e32 v0, v105, v0
	v_exp_f32_e32 v101, v1
	v_sub_f32_e32 v1, v13, v0
	v_add_f32_e32 v0, v104, v0
	v_sub_f32_e32 v0, v12, v0
	v_exp_f32_e32 v102, v1
	v_exp_f32_e32 v103, v0
	v_cvt_pk_bf16_f32 v0, v2, v8
	v_cvt_pk_bf16_f32 v1, v6, v5
	v_cvt_pk_bf16_f32 v2, v21, v20
	v_cvt_pk_bf16_f32 v3, v10, v3
	s_nop 1
	v_mfma_f32_32x32x16_bf16 v[16:31], v[16:19], v[0:3], 0
	v_mfma_f32_32x32x16_bf16 v[0:15], v[44:47], v[0:3], 0
	v_cvt_pk_bf16_f32 v44, v98, v99
	v_cvt_pk_bf16_f32 v45, v97, v96
	v_cvt_pk_bf16_f32 v46, v103, v102
	v_cvt_pk_bf16_f32 v47, v101, v100
	s_nop 1
	v_mfma_f32_32x32x16_bf16 v[16:31], v[36:39], v[44:47], v[16:31]
	v_mfma_f32_32x32x16_bf16 v[0:15], v[40:43], v[44:47], v[0:15]
	s_and_saveexec_b64 s[4:5], s[36:37]
	s_cbranch_execz .LBB0_188
	v_add_f32_e32 v36, v93, v95
	v_add_f32_e32 v36, v36, v94
	s_mov_b32 s2, 0x43170000
	v_cmp_lt_f32_e64 s[36:37], s2, v36
	s_cmp_eq_u64 s[36:37], exec
	s_cbranch_scc1 .LBB0_188
	v_lshrrev_b32_e32 v37, 6, v92
	v_add_f32_e32 v140, 0, v36
	v_add_u16_e32 v36, s9, v37
	v_and_b32_e32 v36, 0xff, v36
	v_not_b32_e32 v37, 63
	v_mov_b64_e32 v[94:95], v[82:83]
	v_mov_b64_e32 v[98:99], v[86:87]
	v_mov_b64_e32 v[102:103], v[90:91]
	v_mov_b64_e32 v[106:107], v[34:35]
	v_lshl_add_u32 v176, v36, 5, v37
	s_mov_b64 s[38:39], 0
	v_mov_b64_e32 v[92:93], v[80:81]
	v_mov_b64_e32 v[96:97], v[84:85]
	v_mov_b64_e32 v[100:101], v[88:89]
	v_mov_b64_e32 v[104:105], v[32:33]
	s_branch .LBB0_301
